# start-up grid sync: dropped the all-wave L1 invalidate in front of it and thread 0's repeated L2 write-back (the all-wave write-back and wait stay)
# speedup vs baseline: 1.0254x; 1.0254x over previous
.LBB0_3:
	s_or_b64 exec, exec, s[4:5]
	v_cmp_gt_i32_e32 vcc, 32, v2
	s_and_saveexec_b64 s[4:5], vcc
	v_lshl_add_u32 v3, v2, 2, 0
	v_add_u32_e32 v3, 0x22000, v3
	v_mov_b32_e32 v4, 0
	ds_write_b32 v3, v4
	s_or_b64 exec, exec, s[4:5]
	v_lshrrev_b32_e32 v3, 20, v0
	v_lshrrev_b32_e32 v0, 10, v0
	v_or_b32_e32 v0, v0, v3
	s_movk_i32 s4, 0x3ff
	v_and_or_b32 v0, v0, s4, v1
	v_cmp_eq_u32_e32 vcc, 0, v0
	buffer_wbl2 sc1
	s_waitcnt vmcnt(0) lgkmcnt(0)
	s_barrier
	s_and_saveexec_b64 s[4:5], vcc
	s_cbranch_execz .LBB0_15
	s_load_dwordx2 s[2:3], s[2:3], 0x58
	v_mov_b32_e32 v4, 0
	s_mov_b64 s[6:7], exec
	v_mbcnt_lo_u32_b32 v3, s6, 0
	v_mbcnt_hi_u32_b32 v3, s7, v3
	s_waitcnt lgkmcnt(0)
	global_load_dword v0, v4, s[2:3] offset:40
	v_cmp_eq_u32_e32 vcc, 0, v3
	s_and_saveexec_b64 s[8:9], vcc
	s_cbranch_execz .LBB0_8
	s_bcnt1_i32_b64 s6, s[6:7]
	v_mov_b32_e32 v5, s6
	global_atomic_add v5, v4, v5, s[2:3] offset:32 sc0
